# adaLN inner loop: 64 rows of ada_w in flight (two batches of 32), non-temporal
# baseline (speedup 1.0000x reference)
; __device__ __forceinline__ void prologue(const __attribute__((address_space(4))) Args& a, ldsp lds, int gw, int NGW, int wave, int lane, const int tid, const int bid, const int G) {
;     ...
;     for (int u = bid; u < 4 * 96; u += G) {
;         const int layer = u / 96, col0 = (u % 96) * 64;
;         const float* Wl = a.ada_w + (size_t)layer * D * NMOD + col0 + lane;
;         float acc[9];
; #pragma unroll
;         for (int j = 0; j < 9; ++j) acc[j] = 0.f;
;         for (int k = wave * 128; k < wave * 128 + 128; k += 16) {
;             float wv[16];
; #pragma unroll
;             for (int q = 0; q < 16; ++q) wv[q] = Wl[(size_t)(k + q) * NMOD];
.LBB0_1277:
	s_mul_hi_i32 s6, s96, 0x2aaaaaab
	s_lshr_b32 s7, s6, 31
	s_ashr_i32 s6, s6, 4
	s_add_i32 s12, s6, s7
	s_mul_i32 s6, s12, 0x60
	s_sub_i32 s6, s96, s6
	s_lshl_b32 s6, s6, 6
	s_ashr_i32 s7, s6, 31
	s_mul_i32 s14, s12, 0x1800000
	s_lshl_b64 s[8:9], s[6:7], 2
	s_mul_hi_i32 s13, s12, 0x1800000
	s_add_u32 s8, s14, s8
	s_addc_u32 s9, s13, s9
	v_mov_b32_e32 v78, 0
	v_lshl_add_u64 v[76:77], v[74:75], 0, s[8:9]
	s_mov_b32 s8, s3
	s_mov_b32 s9, s1
	v_mov_b32_e32 v79, v78
	v_mov_b32_e32 v84, v78
	v_mov_b32_e32 v85, v78
	v_mov_b32_e32 v82, v78
	v_mov_b32_e32 v83, v78
	v_mov_b32_e32 v80, v78
	v_mov_b32_e32 v81, v78
	v_mov_b32_e32 v92, v78
	v_readfirstlane_b32 s22, v76
	v_readfirstlane_b32 s23, v77
	v_lshlrev_b32_e32 v0, 2, v87
	v_mov_b32_e32 v1, s8
	s_sub_u32 s22, s22, 0x5a000
	s_subb_u32 s23, s23, 0
	s_nop 1
	global_load_dword v2, v0, s[22:23] nt
	s_add_u32 s22, s22, 0x6000
	s_addc_u32 s23, s23, 0
	global_load_dword v3, v0, s[22:23] nt
	s_add_u32 s22, s22, 0x6000
	s_addc_u32 s23, s23, 0
	global_load_dword v4, v0, s[22:23] nt
	s_add_u32 s22, s22, 0x6000
	s_addc_u32 s23, s23, 0
	global_load_dword v5, v0, s[22:23] nt
	s_add_u32 s22, s22, 0x6000
	s_addc_u32 s23, s23, 0
	global_load_dword v6, v0, s[22:23] nt
	s_add_u32 s22, s22, 0x6000
	s_addc_u32 s23, s23, 0
	global_load_dword v7, v0, s[22:23] nt
	s_add_u32 s22, s22, 0x6000
	s_addc_u32 s23, s23, 0
	global_load_dword v8, v0, s[22:23] nt
	s_add_u32 s22, s22, 0x6000
	s_addc_u32 s23, s23, 0
	global_load_dword v9, v0, s[22:23] nt
	s_add_u32 s22, s22, 0x6000
	s_addc_u32 s23, s23, 0
	global_load_dword v10, v0, s[22:23] nt
	s_add_u32 s22, s22, 0x6000
	s_addc_u32 s23, s23, 0
	global_load_dword v11, v0, s[22:23] nt
	s_add_u32 s22, s22, 0x6000
	s_addc_u32 s23, s23, 0
	global_load_dword v12, v0, s[22:23] nt
	s_add_u32 s22, s22, 0x6000
	s_addc_u32 s23, s23, 0
	global_load_dword v13, v0, s[22:23] nt
	s_add_u32 s22, s22, 0x6000
	s_addc_u32 s23, s23, 0
	global_load_dword v14, v0, s[22:23] nt
	s_add_u32 s22, s22, 0x6000
	s_addc_u32 s23, s23, 0
	global_load_dword v15, v0, s[22:23] nt
	s_add_u32 s22, s22, 0x6000
	s_addc_u32 s23, s23, 0
	global_load_dword v16, v0, s[22:23] nt
	s_add_u32 s22, s22, 0x6000
	s_addc_u32 s23, s23, 0
	global_load_dword v17, v0, s[22:23] nt
	s_add_u32 s22, s22, 0x6000
	s_addc_u32 s23, s23, 0
	global_load_dword v18, v0, s[22:23] nt
	s_add_u32 s22, s22, 0x6000
	s_addc_u32 s23, s23, 0
	global_load_dword v19, v0, s[22:23] nt
	s_add_u32 s22, s22, 0x6000
	s_addc_u32 s23, s23, 0
	global_load_dword v20, v0, s[22:23] nt
	s_add_u32 s22, s22, 0x6000
	s_addc_u32 s23, s23, 0
	global_load_dword v21, v0, s[22:23] nt
	s_add_u32 s22, s22, 0x6000
	s_addc_u32 s23, s23, 0
	global_load_dword v22, v0, s[22:23] nt
	s_add_u32 s22, s22, 0x6000
	s_addc_u32 s23, s23, 0
	global_load_dword v23, v0, s[22:23] nt
	s_add_u32 s22, s22, 0x6000
	s_addc_u32 s23, s23, 0
	global_load_dword v24, v0, s[22:23] nt
	s_add_u32 s22, s22, 0x6000
	s_addc_u32 s23, s23, 0
	global_load_dword v25, v0, s[22:23] nt
	s_add_u32 s22, s22, 0x6000
	s_addc_u32 s23, s23, 0
	global_load_dword v26, v0, s[22:23] nt
	s_add_u32 s22, s22, 0x6000
	s_addc_u32 s23, s23, 0
	global_load_dword v27, v0, s[22:23] nt
	s_add_u32 s22, s22, 0x6000
	s_addc_u32 s23, s23, 0
	global_load_dword v28, v0, s[22:23] nt
	s_add_u32 s22, s22, 0x6000
	s_addc_u32 s23, s23, 0
	global_load_dword v29, v0, s[22:23] nt
	s_add_u32 s22, s22, 0x6000
	s_addc_u32 s23, s23, 0
	global_load_dword v30, v0, s[22:23] nt
	s_add_u32 s22, s22, 0x6000
	s_addc_u32 s23, s23, 0
	global_load_dword v31, v0, s[22:23] nt
	s_add_u32 s22, s22, 0x6000
	s_addc_u32 s23, s23, 0
	global_load_dword v32, v0, s[22:23] nt
	s_add_u32 s22, s22, 0x6000
	s_addc_u32 s23, s23, 0
	global_load_dword v33, v0, s[22:23] nt
	s_add_u32 s22, s22, 0x6000
	s_addc_u32 s23, s23, 0
	ds_read_b128 v[98:101], v1 offset:0
	ds_read_b128 v[102:105], v1 offset:4096
	ds_read_b128 v[106:109], v1 offset:8192
	ds_read_b128 v[110:113], v1 offset:12288
	ds_read_b128 v[114:117], v1 offset:16384
	ds_read_b128 v[118:121], v1 offset:20480
	ds_read_b128 v[122:125], v1 offset:24576
	ds_read_b128 v[126:129], v1 offset:28672
	ds_read_b128 v[130:133], v1 offset:32768
	global_load_dword v34, v0, s[22:23] nt
	s_add_u32 s22, s22, 0x6000
	s_addc_u32 s23, s23, 0
	global_load_dword v35, v0, s[22:23] nt
	s_add_u32 s22, s22, 0x6000
	s_addc_u32 s23, s23, 0
	global_load_dword v36, v0, s[22:23] nt
	s_add_u32 s22, s22, 0x6000
	s_addc_u32 s23, s23, 0
	global_load_dword v37, v0, s[22:23] nt
	s_add_u32 s22, s22, 0x6000
	s_addc_u32 s23, s23, 0
	global_load_dword v38, v0, s[22:23] nt
	s_add_u32 s22, s22, 0x6000
	s_addc_u32 s23, s23, 0
	global_load_dword v39, v0, s[22:23] nt
	s_add_u32 s22, s22, 0x6000
	s_addc_u32 s23, s23, 0
	global_load_dword v40, v0, s[22:23] nt
	s_add_u32 s22, s22, 0x6000
	s_addc_u32 s23, s23, 0
	global_load_dword v41, v0, s[22:23] nt
	s_add_u32 s22, s22, 0x6000
	s_addc_u32 s23, s23, 0
	global_load_dword v42, v0, s[22:23] nt
	s_add_u32 s22, s22, 0x6000
	s_addc_u32 s23, s23, 0
	global_load_dword v43, v0, s[22:23] nt
	s_add_u32 s22, s22, 0x6000
	s_addc_u32 s23, s23, 0
	global_load_dword v44, v0, s[22:23] nt
	s_add_u32 s22, s22, 0x6000
	s_addc_u32 s23, s23, 0
	global_load_dword v45, v0, s[22:23] nt
	s_add_u32 s22, s22, 0x6000
	s_addc_u32 s23, s23, 0
	global_load_dword v46, v0, s[22:23] nt
	s_add_u32 s22, s22, 0x6000
	s_addc_u32 s23, s23, 0
	global_load_dword v47, v0, s[22:23] nt
	s_add_u32 s22, s22, 0x6000
	s_addc_u32 s23, s23, 0
	global_load_dword v48, v0, s[22:23] nt
	s_add_u32 s22, s22, 0x6000
	s_addc_u32 s23, s23, 0
	global_load_dword v49, v0, s[22:23] nt
	s_add_u32 s22, s22, 0x6000
	s_addc_u32 s23, s23, 0
	global_load_dword v50, v0, s[22:23] nt
; #define LAS __attribute__((address_space(3)))
; __device__ __forceinline__ void prologue(const __attribute__((address_space(4))) Args& a, ldsp lds, int gw, int NGW, int wave, int lane, const int tid, const int bid, const int G) {
;     ...
;         for (int k = wave * 128; k < wave * 128 + 128; k += 16) {
;             float wv[16];
; #pragma unroll
;             for (int q = 0; q < 16; ++q) wv[q] = Wl[(size_t)(k + q) * NMOD];
; #pragma unroll
;             for (int q4 = 0; q4 < 4; ++q4)
; #pragma unroll
;                 for (int j = 0; j < 9; ++j) { const f32x4 s4 = *(const LAS f32x4*)(sc + j * D + k + 4 * q4); acc[j] += s4[0] * wv[4 * q4] + s4[1] * wv[4 * q4 + 1] + s4[2] * wv[4 * q4 + 2] + s4[3] * wv[4 * q4 + 3]; }
	s_add_u32 s22, s22, 0x6000
	s_addc_u32 s23, s23, 0
	global_load_dword v51, v0, s[22:23] nt
	s_add_u32 s22, s22, 0x6000
	s_addc_u32 s23, s23, 0
	global_load_dword v52, v0, s[22:23] nt
	s_add_u32 s22, s22, 0x6000
	s_addc_u32 s23, s23, 0
	global_load_dword v53, v0, s[22:23] nt
	s_add_u32 s22, s22, 0x6000
	s_addc_u32 s23, s23, 0
	global_load_dword v54, v0, s[22:23] nt
	s_add_u32 s22, s22, 0x6000
	s_addc_u32 s23, s23, 0
	global_load_dword v55, v0, s[22:23] nt
	s_add_u32 s22, s22, 0x6000
	s_addc_u32 s23, s23, 0
	global_load_dword v56, v0, s[22:23] nt
	s_add_u32 s22, s22, 0x6000
	s_addc_u32 s23, s23, 0
	global_load_dword v57, v0, s[22:23] nt
	s_add_u32 s22, s22, 0x6000
	s_addc_u32 s23, s23, 0
	global_load_dword v58, v0, s[22:23] nt
	s_add_u32 s22, s22, 0x6000
	s_addc_u32 s23, s23, 0
	global_load_dword v59, v0, s[22:23] nt
	s_add_u32 s22, s22, 0x6000
	s_addc_u32 s23, s23, 0
	global_load_dword v60, v0, s[22:23] nt
	s_add_u32 s22, s22, 0x6000
	s_addc_u32 s23, s23, 0
	global_load_dword v61, v0, s[22:23] nt
	s_add_u32 s22, s22, 0x6000
	s_addc_u32 s23, s23, 0
	global_load_dword v62, v0, s[22:23] nt
	s_add_u32 s22, s22, 0x6000
	s_addc_u32 s23, s23, 0
	global_load_dword v63, v0, s[22:23] nt
	s_add_u32 s22, s22, 0x6000
	s_addc_u32 s23, s23, 0
	global_load_dword v64, v0, s[22:23] nt
	s_add_u32 s22, s22, 0x6000
	s_addc_u32 s23, s23, 0
	global_load_dword v65, v0, s[22:23] nt
	s_add_u32 s22, s22, 0x6000
	s_addc_u32 s23, s23, 0
	v_mov_b64_e32 v[226:227], 0
	v_mov_b64_e32 v[228:229], 0
	v_mov_b64_e32 v[230:231], 0
	v_mov_b64_e32 v[232:233], 0
	v_mov_b64_e32 v[234:235], 0
	v_mov_b64_e32 v[236:237], 0
	v_mov_b64_e32 v[238:239], 0
	v_mov_b64_e32 v[240:241], 0
	v_mov_b64_e32 v[242:243], 0
	s_waitcnt vmcnt(32)
	ds_read_b128 v[134:137], v1 offset:16
	ds_read_b128 v[138:141], v1 offset:4112
	ds_read_b128 v[142:145], v1 offset:8208
	ds_read_b128 v[146:149], v1 offset:12304
	ds_read_b128 v[150:153], v1 offset:16400
	ds_read_b128 v[154:157], v1 offset:20496
	ds_read_b128 v[158:161], v1 offset:24592
	ds_read_b128 v[162:165], v1 offset:28688
	ds_read_b128 v[166:169], v1 offset:32784
	s_waitcnt lgkmcnt(9)
	v_pk_fma_f32 v[226:227], v[98:99], v[2:3], v[226:227]
	v_pk_fma_f32 v[228:229], v[102:103], v[2:3], v[228:229]
	v_pk_fma_f32 v[230:231], v[106:107], v[2:3], v[230:231]
	v_pk_fma_f32 v[232:233], v[110:111], v[2:3], v[232:233]
	v_pk_fma_f32 v[234:235], v[114:115], v[2:3], v[234:235]
	v_pk_fma_f32 v[236:237], v[118:119], v[2:3], v[236:237]
	v_pk_fma_f32 v[238:239], v[122:123], v[2:3], v[238:239]
	v_pk_fma_f32 v[240:241], v[126:127], v[2:3], v[240:241]
	v_pk_fma_f32 v[242:243], v[130:131], v[2:3], v[242:243]
	v_pk_fma_f32 v[226:227], v[100:101], v[4:5], v[226:227]
	v_pk_fma_f32 v[228:229], v[104:105], v[4:5], v[228:229]
	v_pk_fma_f32 v[230:231], v[108:109], v[4:5], v[230:231]
	v_pk_fma_f32 v[232:233], v[112:113], v[4:5], v[232:233]
	v_pk_fma_f32 v[234:235], v[116:117], v[4:5], v[234:235]
	v_pk_fma_f32 v[236:237], v[120:121], v[4:5], v[236:237]
	v_pk_fma_f32 v[238:239], v[124:125], v[4:5], v[238:239]
	v_pk_fma_f32 v[240:241], v[128:129], v[4:5], v[240:241]
	v_pk_fma_f32 v[242:243], v[132:133], v[4:5], v[242:243]
	ds_read_b128 v[98:101], v1 offset:32
	ds_read_b128 v[102:105], v1 offset:4128
	ds_read_b128 v[106:109], v1 offset:8224
	ds_read_b128 v[110:113], v1 offset:12320
	ds_read_b128 v[114:117], v1 offset:16416
	ds_read_b128 v[118:121], v1 offset:20512
	ds_read_b128 v[122:125], v1 offset:24608
	ds_read_b128 v[126:129], v1 offset:28704
	ds_read_b128 v[130:133], v1 offset:32800
	s_waitcnt lgkmcnt(9)
	v_pk_fma_f32 v[226:227], v[134:135], v[6:7], v[226:227]
	v_pk_fma_f32 v[228:229], v[138:139], v[6:7], v[228:229]
	v_pk_fma_f32 v[230:231], v[142:143], v[6:7], v[230:231]
	v_pk_fma_f32 v[232:233], v[146:147], v[6:7], v[232:233]
	v_pk_fma_f32 v[234:235], v[150:151], v[6:7], v[234:235]
	v_pk_fma_f32 v[236:237], v[154:155], v[6:7], v[236:237]
	v_pk_fma_f32 v[238:239], v[158:159], v[6:7], v[238:239]
	v_pk_fma_f32 v[240:241], v[162:163], v[6:7], v[240:241]
	v_pk_fma_f32 v[242:243], v[166:167], v[6:7], v[242:243]
	v_pk_fma_f32 v[226:227], v[136:137], v[8:9], v[226:227]
	v_pk_fma_f32 v[228:229], v[140:141], v[8:9], v[228:229]
	v_pk_fma_f32 v[230:231], v[144:145], v[8:9], v[230:231]
	v_pk_fma_f32 v[232:233], v[148:149], v[8:9], v[232:233]
	v_pk_fma_f32 v[234:235], v[152:153], v[8:9], v[234:235]
	v_pk_fma_f32 v[236:237], v[156:157], v[8:9], v[236:237]
	v_pk_fma_f32 v[238:239], v[160:161], v[8:9], v[238:239]
	v_pk_fma_f32 v[240:241], v[164:165], v[8:9], v[240:241]
	v_pk_fma_f32 v[242:243], v[168:169], v[8:9], v[242:243]
	ds_read_b128 v[134:137], v1 offset:48
	ds_read_b128 v[138:141], v1 offset:4144
	ds_read_b128 v[142:145], v1 offset:8240
	ds_read_b128 v[146:149], v1 offset:12336
	ds_read_b128 v[150:153], v1 offset:16432
	ds_read_b128 v[154:157], v1 offset:20528
	ds_read_b128 v[158:161], v1 offset:24624
	ds_read_b128 v[162:165], v1 offset:28720
	ds_read_b128 v[166:169], v1 offset:32816
	s_waitcnt lgkmcnt(9)
; #define LAS __attribute__((address_space(3)))
; __device__ __forceinline__ void prologue(const __attribute__((address_space(4))) Args& a, ldsp lds, int gw, int NGW, int wave, int lane, const int tid, const int bid, const int G) {
;     ...
;             for (int q = 0; q < 16; ++q) wv[q] = Wl[(size_t)(k + q) * NMOD];
; #pragma unroll
;             for (int q4 = 0; q4 < 4; ++q4)
; #pragma unroll
;                 for (int j = 0; j < 9; ++j) { const f32x4 s4 = *(const LAS f32x4*)(sc + j * D + k + 4 * q4); acc[j] += s4[0] * wv[4 * q4] + s4[1] * wv[4 * q4 + 1] + s4[2] * wv[4 * q4 + 2] + s4[3] * wv[4 * q4 + 3]; }
	v_pk_fma_f32 v[226:227], v[98:99], v[10:11], v[226:227]
	v_pk_fma_f32 v[228:229], v[102:103], v[10:11], v[228:229]
	v_pk_fma_f32 v[230:231], v[106:107], v[10:11], v[230:231]
	v_pk_fma_f32 v[232:233], v[110:111], v[10:11], v[232:233]
	v_pk_fma_f32 v[234:235], v[114:115], v[10:11], v[234:235]
	v_pk_fma_f32 v[236:237], v[118:119], v[10:11], v[236:237]
	v_pk_fma_f32 v[238:239], v[122:123], v[10:11], v[238:239]
	v_pk_fma_f32 v[240:241], v[126:127], v[10:11], v[240:241]
	v_pk_fma_f32 v[242:243], v[130:131], v[10:11], v[242:243]
	v_pk_fma_f32 v[226:227], v[100:101], v[12:13], v[226:227]
	v_pk_fma_f32 v[228:229], v[104:105], v[12:13], v[228:229]
	v_pk_fma_f32 v[230:231], v[108:109], v[12:13], v[230:231]
	v_pk_fma_f32 v[232:233], v[112:113], v[12:13], v[232:233]
	v_pk_fma_f32 v[234:235], v[116:117], v[12:13], v[234:235]
	v_pk_fma_f32 v[236:237], v[120:121], v[12:13], v[236:237]
	v_pk_fma_f32 v[238:239], v[124:125], v[12:13], v[238:239]
	v_pk_fma_f32 v[240:241], v[128:129], v[12:13], v[240:241]
	v_pk_fma_f32 v[242:243], v[132:133], v[12:13], v[242:243]
	ds_read_b128 v[98:101], v1 offset:64
	ds_read_b128 v[102:105], v1 offset:4160
	ds_read_b128 v[106:109], v1 offset:8256
	ds_read_b128 v[110:113], v1 offset:12352
	ds_read_b128 v[114:117], v1 offset:16448
	ds_read_b128 v[118:121], v1 offset:20544
	ds_read_b128 v[122:125], v1 offset:24640
	ds_read_b128 v[126:129], v1 offset:28736
	ds_read_b128 v[130:133], v1 offset:32832
	s_waitcnt lgkmcnt(9)
	v_pk_fma_f32 v[226:227], v[134:135], v[14:15], v[226:227]
	v_pk_fma_f32 v[228:229], v[138:139], v[14:15], v[228:229]
	v_pk_fma_f32 v[230:231], v[142:143], v[14:15], v[230:231]
	v_pk_fma_f32 v[232:233], v[146:147], v[14:15], v[232:233]
	v_pk_fma_f32 v[234:235], v[150:151], v[14:15], v[234:235]
	v_pk_fma_f32 v[236:237], v[154:155], v[14:15], v[236:237]
	v_pk_fma_f32 v[238:239], v[158:159], v[14:15], v[238:239]
	v_pk_fma_f32 v[240:241], v[162:163], v[14:15], v[240:241]
	v_pk_fma_f32 v[242:243], v[166:167], v[14:15], v[242:243]
	v_pk_fma_f32 v[226:227], v[136:137], v[16:17], v[226:227]
	v_pk_fma_f32 v[228:229], v[140:141], v[16:17], v[228:229]
	v_pk_fma_f32 v[230:231], v[144:145], v[16:17], v[230:231]
	v_pk_fma_f32 v[232:233], v[148:149], v[16:17], v[232:233]
	v_pk_fma_f32 v[234:235], v[152:153], v[16:17], v[234:235]
	v_pk_fma_f32 v[236:237], v[156:157], v[16:17], v[236:237]
	v_pk_fma_f32 v[238:239], v[160:161], v[16:17], v[238:239]
	v_pk_fma_f32 v[240:241], v[164:165], v[16:17], v[240:241]
	v_pk_fma_f32 v[242:243], v[168:169], v[16:17], v[242:243]
	ds_read_b128 v[134:137], v1 offset:80
	ds_read_b128 v[138:141], v1 offset:4176
	ds_read_b128 v[142:145], v1 offset:8272
	ds_read_b128 v[146:149], v1 offset:12368
	ds_read_b128 v[150:153], v1 offset:16464
	ds_read_b128 v[154:157], v1 offset:20560
	ds_read_b128 v[158:161], v1 offset:24656
	ds_read_b128 v[162:165], v1 offset:28752
	ds_read_b128 v[166:169], v1 offset:32848
	s_waitcnt lgkmcnt(9)
	v_pk_fma_f32 v[226:227], v[98:99], v[18:19], v[226:227]
	v_pk_fma_f32 v[228:229], v[102:103], v[18:19], v[228:229]
	v_pk_fma_f32 v[230:231], v[106:107], v[18:19], v[230:231]
	v_pk_fma_f32 v[232:233], v[110:111], v[18:19], v[232:233]
	v_pk_fma_f32 v[234:235], v[114:115], v[18:19], v[234:235]
	v_pk_fma_f32 v[236:237], v[118:119], v[18:19], v[236:237]
	v_pk_fma_f32 v[238:239], v[122:123], v[18:19], v[238:239]
	v_pk_fma_f32 v[240:241], v[126:127], v[18:19], v[240:241]
	v_pk_fma_f32 v[242:243], v[130:131], v[18:19], v[242:243]
	v_pk_fma_f32 v[226:227], v[100:101], v[20:21], v[226:227]
	v_pk_fma_f32 v[228:229], v[104:105], v[20:21], v[228:229]
	v_pk_fma_f32 v[230:231], v[108:109], v[20:21], v[230:231]
	v_pk_fma_f32 v[232:233], v[112:113], v[20:21], v[232:233]
	v_pk_fma_f32 v[234:235], v[116:117], v[20:21], v[234:235]
	v_pk_fma_f32 v[236:237], v[120:121], v[20:21], v[236:237]
	v_pk_fma_f32 v[238:239], v[124:125], v[20:21], v[238:239]
	v_pk_fma_f32 v[240:241], v[128:129], v[20:21], v[240:241]
	v_pk_fma_f32 v[242:243], v[132:133], v[20:21], v[242:243]
	ds_read_b128 v[98:101], v1 offset:96
	ds_read_b128 v[102:105], v1 offset:4192
	ds_read_b128 v[106:109], v1 offset:8288
	ds_read_b128 v[110:113], v1 offset:12384
	ds_read_b128 v[114:117], v1 offset:16480
	ds_read_b128 v[118:121], v1 offset:20576
	ds_read_b128 v[122:125], v1 offset:24672
	ds_read_b128 v[126:129], v1 offset:28768
	ds_read_b128 v[130:133], v1 offset:32864
	s_waitcnt lgkmcnt(9)
	v_pk_fma_f32 v[226:227], v[134:135], v[22:23], v[226:227]
	v_pk_fma_f32 v[228:229], v[138:139], v[22:23], v[228:229]
	v_pk_fma_f32 v[230:231], v[142:143], v[22:23], v[230:231]
	v_pk_fma_f32 v[232:233], v[146:147], v[22:23], v[232:233]
	v_pk_fma_f32 v[234:235], v[150:151], v[22:23], v[234:235]
	v_pk_fma_f32 v[236:237], v[154:155], v[22:23], v[236:237]
	v_pk_fma_f32 v[238:239], v[158:159], v[22:23], v[238:239]
	v_pk_fma_f32 v[240:241], v[162:163], v[22:23], v[240:241]
	v_pk_fma_f32 v[242:243], v[166:167], v[22:23], v[242:243]
	v_pk_fma_f32 v[226:227], v[136:137], v[24:25], v[226:227]
	v_pk_fma_f32 v[228:229], v[140:141], v[24:25], v[228:229]
	v_pk_fma_f32 v[230:231], v[144:145], v[24:25], v[230:231]
	v_pk_fma_f32 v[232:233], v[148:149], v[24:25], v[232:233]
	v_pk_fma_f32 v[234:235], v[152:153], v[24:25], v[234:235]
	v_pk_fma_f32 v[236:237], v[156:157], v[24:25], v[236:237]
	v_pk_fma_f32 v[238:239], v[160:161], v[24:25], v[238:239]
	v_pk_fma_f32 v[240:241], v[164:165], v[24:25], v[240:241]
	v_pk_fma_f32 v[242:243], v[168:169], v[24:25], v[242:243]
	ds_read_b128 v[134:137], v1 offset:112
	ds_read_b128 v[138:141], v1 offset:4208
	ds_read_b128 v[142:145], v1 offset:8304
	ds_read_b128 v[146:149], v1 offset:12400
	ds_read_b128 v[150:153], v1 offset:16496
	ds_read_b128 v[154:157], v1 offset:20592
	ds_read_b128 v[158:161], v1 offset:24688
	ds_read_b128 v[162:165], v1 offset:28784
	ds_read_b128 v[166:169], v1 offset:32880
	s_waitcnt lgkmcnt(9)
; #define LAS __attribute__((address_space(3)))
; __device__ __forceinline__ void prologue(const __attribute__((address_space(4))) Args& a, ldsp lds, int gw, int NGW, int wave, int lane, const int tid, const int bid, const int G) {
;     ...
;             for (int q = 0; q < 16; ++q) wv[q] = Wl[(size_t)(k + q) * NMOD];
; #pragma unroll
;             for (int q4 = 0; q4 < 4; ++q4)
; #pragma unroll
;                 for (int j = 0; j < 9; ++j) { const f32x4 s4 = *(const LAS f32x4*)(sc + j * D + k + 4 * q4); acc[j] += s4[0] * wv[4 * q4] + s4[1] * wv[4 * q4 + 1] + s4[2] * wv[4 * q4 + 2] + s4[3] * wv[4 * q4 + 3]; }
	v_pk_fma_f32 v[226:227], v[98:99], v[26:27], v[226:227]
	v_pk_fma_f32 v[228:229], v[102:103], v[26:27], v[228:229]
	v_pk_fma_f32 v[230:231], v[106:107], v[26:27], v[230:231]
	v_pk_fma_f32 v[232:233], v[110:111], v[26:27], v[232:233]
	v_pk_fma_f32 v[234:235], v[114:115], v[26:27], v[234:235]
	v_pk_fma_f32 v[236:237], v[118:119], v[26:27], v[236:237]
	v_pk_fma_f32 v[238:239], v[122:123], v[26:27], v[238:239]
	v_pk_fma_f32 v[240:241], v[126:127], v[26:27], v[240:241]
	v_pk_fma_f32 v[242:243], v[130:131], v[26:27], v[242:243]
	v_pk_fma_f32 v[226:227], v[100:101], v[28:29], v[226:227]
	v_pk_fma_f32 v[228:229], v[104:105], v[28:29], v[228:229]
	v_pk_fma_f32 v[230:231], v[108:109], v[28:29], v[230:231]
	v_pk_fma_f32 v[232:233], v[112:113], v[28:29], v[232:233]
	v_pk_fma_f32 v[234:235], v[116:117], v[28:29], v[234:235]
	v_pk_fma_f32 v[236:237], v[120:121], v[28:29], v[236:237]
	v_pk_fma_f32 v[238:239], v[124:125], v[28:29], v[238:239]
	v_pk_fma_f32 v[240:241], v[128:129], v[28:29], v[240:241]
	v_pk_fma_f32 v[242:243], v[132:133], v[28:29], v[242:243]
	ds_read_b128 v[98:101], v1 offset:128
	ds_read_b128 v[102:105], v1 offset:4224
	ds_read_b128 v[106:109], v1 offset:8320
	ds_read_b128 v[110:113], v1 offset:12416
	ds_read_b128 v[114:117], v1 offset:16512
	ds_read_b128 v[118:121], v1 offset:20608
	ds_read_b128 v[122:125], v1 offset:24704
	ds_read_b128 v[126:129], v1 offset:28800
	ds_read_b128 v[130:133], v1 offset:32896
	s_waitcnt lgkmcnt(9)
	v_pk_fma_f32 v[226:227], v[134:135], v[30:31], v[226:227]
	v_pk_fma_f32 v[228:229], v[138:139], v[30:31], v[228:229]
	v_pk_fma_f32 v[230:231], v[142:143], v[30:31], v[230:231]
	v_pk_fma_f32 v[232:233], v[146:147], v[30:31], v[232:233]
	v_pk_fma_f32 v[234:235], v[150:151], v[30:31], v[234:235]
	v_pk_fma_f32 v[236:237], v[154:155], v[30:31], v[236:237]
	v_pk_fma_f32 v[238:239], v[158:159], v[30:31], v[238:239]
	v_pk_fma_f32 v[240:241], v[162:163], v[30:31], v[240:241]
	v_pk_fma_f32 v[242:243], v[166:167], v[30:31], v[242:243]
	v_pk_fma_f32 v[226:227], v[136:137], v[32:33], v[226:227]
	v_pk_fma_f32 v[228:229], v[140:141], v[32:33], v[228:229]
	v_pk_fma_f32 v[230:231], v[144:145], v[32:33], v[230:231]
	v_pk_fma_f32 v[232:233], v[148:149], v[32:33], v[232:233]
	v_pk_fma_f32 v[234:235], v[152:153], v[32:33], v[234:235]
	v_pk_fma_f32 v[236:237], v[156:157], v[32:33], v[236:237]
	v_pk_fma_f32 v[238:239], v[160:161], v[32:33], v[238:239]
	v_pk_fma_f32 v[240:241], v[164:165], v[32:33], v[240:241]
	v_pk_fma_f32 v[242:243], v[168:169], v[32:33], v[242:243]
	global_load_dword v2, v0, s[22:23] nt
	s_add_u32 s22, s22, 0x6000
	s_addc_u32 s23, s23, 0
	global_load_dword v3, v0, s[22:23] nt
	s_add_u32 s22, s22, 0x6000
	s_addc_u32 s23, s23, 0
	global_load_dword v4, v0, s[22:23] nt
	s_add_u32 s22, s22, 0x6000
	s_addc_u32 s23, s23, 0
	global_load_dword v5, v0, s[22:23] nt
	s_add_u32 s22, s22, 0x6000
	s_addc_u32 s23, s23, 0
	global_load_dword v6, v0, s[22:23] nt
	s_add_u32 s22, s22, 0x6000
	s_addc_u32 s23, s23, 0
	global_load_dword v7, v0, s[22:23] nt
	s_add_u32 s22, s22, 0x6000
	s_addc_u32 s23, s23, 0
	global_load_dword v8, v0, s[22:23] nt
	s_add_u32 s22, s22, 0x6000
	s_addc_u32 s23, s23, 0
	global_load_dword v9, v0, s[22:23] nt
	s_add_u32 s22, s22, 0x6000
	s_addc_u32 s23, s23, 0
	global_load_dword v10, v0, s[22:23] nt
	s_add_u32 s22, s22, 0x6000
	s_addc_u32 s23, s23, 0
	global_load_dword v11, v0, s[22:23] nt
	s_add_u32 s22, s22, 0x6000
	s_addc_u32 s23, s23, 0
	global_load_dword v12, v0, s[22:23] nt
	s_add_u32 s22, s22, 0x6000
	s_addc_u32 s23, s23, 0
	global_load_dword v13, v0, s[22:23] nt
	s_add_u32 s22, s22, 0x6000
	s_addc_u32 s23, s23, 0
	global_load_dword v14, v0, s[22:23] nt
	s_add_u32 s22, s22, 0x6000
	s_addc_u32 s23, s23, 0
	global_load_dword v15, v0, s[22:23] nt
	s_add_u32 s22, s22, 0x6000
	s_addc_u32 s23, s23, 0
	global_load_dword v16, v0, s[22:23] nt
	s_add_u32 s22, s22, 0x6000
	s_addc_u32 s23, s23, 0
	global_load_dword v17, v0, s[22:23] nt
	s_add_u32 s22, s22, 0x6000
	s_addc_u32 s23, s23, 0
	global_load_dword v18, v0, s[22:23] nt
	s_add_u32 s22, s22, 0x6000
	s_addc_u32 s23, s23, 0
	global_load_dword v19, v0, s[22:23] nt
	s_add_u32 s22, s22, 0x6000
	s_addc_u32 s23, s23, 0
	global_load_dword v20, v0, s[22:23] nt
	s_add_u32 s22, s22, 0x6000
	s_addc_u32 s23, s23, 0
	global_load_dword v21, v0, s[22:23] nt
	s_add_u32 s22, s22, 0x6000
	s_addc_u32 s23, s23, 0
	global_load_dword v22, v0, s[22:23] nt
	s_add_u32 s22, s22, 0x6000
	s_addc_u32 s23, s23, 0
	global_load_dword v23, v0, s[22:23] nt
	s_add_u32 s22, s22, 0x6000
	s_addc_u32 s23, s23, 0
	global_load_dword v24, v0, s[22:23] nt
	s_add_u32 s22, s22, 0x6000
	s_addc_u32 s23, s23, 0
	global_load_dword v25, v0, s[22:23] nt
	s_add_u32 s22, s22, 0x6000
	s_addc_u32 s23, s23, 0
	global_load_dword v26, v0, s[22:23] nt
	s_add_u32 s22, s22, 0x6000
	s_addc_u32 s23, s23, 0
	global_load_dword v27, v0, s[22:23] nt
	s_add_u32 s22, s22, 0x6000
	s_addc_u32 s23, s23, 0
	global_load_dword v28, v0, s[22:23] nt
	s_add_u32 s22, s22, 0x6000
	s_addc_u32 s23, s23, 0
	global_load_dword v29, v0, s[22:23] nt
	s_add_u32 s22, s22, 0x6000
	s_addc_u32 s23, s23, 0
	global_load_dword v30, v0, s[22:23] nt
	s_add_u32 s22, s22, 0x6000
	s_addc_u32 s23, s23, 0
	global_load_dword v31, v0, s[22:23] nt
	s_add_u32 s22, s22, 0x6000
	s_addc_u32 s23, s23, 0
	global_load_dword v32, v0, s[22:23] nt
	s_add_u32 s22, s22, 0x6000
	s_addc_u32 s23, s23, 0
	global_load_dword v33, v0, s[22:23] nt
	s_add_u32 s22, s22, 0x6000
	s_addc_u32 s23, s23, 0
	s_waitcnt vmcnt(32)
; #define LAS __attribute__((address_space(3)))
; __device__ __forceinline__ void prologue(const __attribute__((address_space(4))) Args& a, ldsp lds, int gw, int NGW, int wave, int lane, const int tid, const int bid, const int G) {
;     ...
;             for (int q = 0; q < 16; ++q) wv[q] = Wl[(size_t)(k + q) * NMOD];
; #pragma unroll
;             for (int q4 = 0; q4 < 4; ++q4)
; #pragma unroll
;                 for (int j = 0; j < 9; ++j) { const f32x4 s4 = *(const LAS f32x4*)(sc + j * D + k + 4 * q4); acc[j] += s4[0] * wv[4 * q4] + s4[1] * wv[4 * q4 + 1] + s4[2] * wv[4 * q4 + 2] + s4[3] * wv[4 * q4 + 3]; }
	ds_read_b128 v[134:137], v1 offset:144
	ds_read_b128 v[138:141], v1 offset:4240
	ds_read_b128 v[142:145], v1 offset:8336
	ds_read_b128 v[146:149], v1 offset:12432
	ds_read_b128 v[150:153], v1 offset:16528
	ds_read_b128 v[154:157], v1 offset:20624
	ds_read_b128 v[158:161], v1 offset:24720
	ds_read_b128 v[162:165], v1 offset:28816
	ds_read_b128 v[166:169], v1 offset:32912
	s_waitcnt lgkmcnt(9)
	v_pk_fma_f32 v[226:227], v[98:99], v[34:35], v[226:227]
	v_pk_fma_f32 v[228:229], v[102:103], v[34:35], v[228:229]
	v_pk_fma_f32 v[230:231], v[106:107], v[34:35], v[230:231]
	v_pk_fma_f32 v[232:233], v[110:111], v[34:35], v[232:233]
	v_pk_fma_f32 v[234:235], v[114:115], v[34:35], v[234:235]
	v_pk_fma_f32 v[236:237], v[118:119], v[34:35], v[236:237]
	v_pk_fma_f32 v[238:239], v[122:123], v[34:35], v[238:239]
	v_pk_fma_f32 v[240:241], v[126:127], v[34:35], v[240:241]
	v_pk_fma_f32 v[242:243], v[130:131], v[34:35], v[242:243]
	v_pk_fma_f32 v[226:227], v[100:101], v[36:37], v[226:227]
	v_pk_fma_f32 v[228:229], v[104:105], v[36:37], v[228:229]
	v_pk_fma_f32 v[230:231], v[108:109], v[36:37], v[230:231]
	v_pk_fma_f32 v[232:233], v[112:113], v[36:37], v[232:233]
	v_pk_fma_f32 v[234:235], v[116:117], v[36:37], v[234:235]
	v_pk_fma_f32 v[236:237], v[120:121], v[36:37], v[236:237]
	v_pk_fma_f32 v[238:239], v[124:125], v[36:37], v[238:239]
	v_pk_fma_f32 v[240:241], v[128:129], v[36:37], v[240:241]
	v_pk_fma_f32 v[242:243], v[132:133], v[36:37], v[242:243]
	ds_read_b128 v[98:101], v1 offset:160
	ds_read_b128 v[102:105], v1 offset:4256
	ds_read_b128 v[106:109], v1 offset:8352
	ds_read_b128 v[110:113], v1 offset:12448
	ds_read_b128 v[114:117], v1 offset:16544
	ds_read_b128 v[118:121], v1 offset:20640
	ds_read_b128 v[122:125], v1 offset:24736
	ds_read_b128 v[126:129], v1 offset:28832
	ds_read_b128 v[130:133], v1 offset:32928
	s_waitcnt lgkmcnt(9)
	v_pk_fma_f32 v[226:227], v[134:135], v[38:39], v[226:227]
	v_pk_fma_f32 v[228:229], v[138:139], v[38:39], v[228:229]
	v_pk_fma_f32 v[230:231], v[142:143], v[38:39], v[230:231]
	v_pk_fma_f32 v[232:233], v[146:147], v[38:39], v[232:233]
	v_pk_fma_f32 v[234:235], v[150:151], v[38:39], v[234:235]
	v_pk_fma_f32 v[236:237], v[154:155], v[38:39], v[236:237]
	v_pk_fma_f32 v[238:239], v[158:159], v[38:39], v[238:239]
	v_pk_fma_f32 v[240:241], v[162:163], v[38:39], v[240:241]
	v_pk_fma_f32 v[242:243], v[166:167], v[38:39], v[242:243]
	v_pk_fma_f32 v[226:227], v[136:137], v[40:41], v[226:227]
	v_pk_fma_f32 v[228:229], v[140:141], v[40:41], v[228:229]
	v_pk_fma_f32 v[230:231], v[144:145], v[40:41], v[230:231]
	v_pk_fma_f32 v[232:233], v[148:149], v[40:41], v[232:233]
	v_pk_fma_f32 v[234:235], v[152:153], v[40:41], v[234:235]
	v_pk_fma_f32 v[236:237], v[156:157], v[40:41], v[236:237]
	v_pk_fma_f32 v[238:239], v[160:161], v[40:41], v[238:239]
	v_pk_fma_f32 v[240:241], v[164:165], v[40:41], v[240:241]
	v_pk_fma_f32 v[242:243], v[168:169], v[40:41], v[242:243]
	ds_read_b128 v[134:137], v1 offset:176
	ds_read_b128 v[138:141], v1 offset:4272
	ds_read_b128 v[142:145], v1 offset:8368
	ds_read_b128 v[146:149], v1 offset:12464
	ds_read_b128 v[150:153], v1 offset:16560
	ds_read_b128 v[154:157], v1 offset:20656
	ds_read_b128 v[158:161], v1 offset:24752
	ds_read_b128 v[162:165], v1 offset:28848
	ds_read_b128 v[166:169], v1 offset:32944
	s_waitcnt lgkmcnt(9)
	v_pk_fma_f32 v[226:227], v[98:99], v[42:43], v[226:227]
	v_pk_fma_f32 v[228:229], v[102:103], v[42:43], v[228:229]
	v_pk_fma_f32 v[230:231], v[106:107], v[42:43], v[230:231]
	v_pk_fma_f32 v[232:233], v[110:111], v[42:43], v[232:233]
	v_pk_fma_f32 v[234:235], v[114:115], v[42:43], v[234:235]
	v_pk_fma_f32 v[236:237], v[118:119], v[42:43], v[236:237]
	v_pk_fma_f32 v[238:239], v[122:123], v[42:43], v[238:239]
	v_pk_fma_f32 v[240:241], v[126:127], v[42:43], v[240:241]
	v_pk_fma_f32 v[242:243], v[130:131], v[42:43], v[242:243]
	v_pk_fma_f32 v[226:227], v[100:101], v[44:45], v[226:227]
	v_pk_fma_f32 v[228:229], v[104:105], v[44:45], v[228:229]
	v_pk_fma_f32 v[230:231], v[108:109], v[44:45], v[230:231]
	v_pk_fma_f32 v[232:233], v[112:113], v[44:45], v[232:233]
	v_pk_fma_f32 v[234:235], v[116:117], v[44:45], v[234:235]
	v_pk_fma_f32 v[236:237], v[120:121], v[44:45], v[236:237]
	v_pk_fma_f32 v[238:239], v[124:125], v[44:45], v[238:239]
	v_pk_fma_f32 v[240:241], v[128:129], v[44:45], v[240:241]
	v_pk_fma_f32 v[242:243], v[132:133], v[44:45], v[242:243]
	ds_read_b128 v[98:101], v1 offset:192
	ds_read_b128 v[102:105], v1 offset:4288
	ds_read_b128 v[106:109], v1 offset:8384
	ds_read_b128 v[110:113], v1 offset:12480
	ds_read_b128 v[114:117], v1 offset:16576
	ds_read_b128 v[118:121], v1 offset:20672
	ds_read_b128 v[122:125], v1 offset:24768
	ds_read_b128 v[126:129], v1 offset:28864
	ds_read_b128 v[130:133], v1 offset:32960
	s_waitcnt lgkmcnt(9)
	v_pk_fma_f32 v[226:227], v[134:135], v[46:47], v[226:227]
	v_pk_fma_f32 v[228:229], v[138:139], v[46:47], v[228:229]
	v_pk_fma_f32 v[230:231], v[142:143], v[46:47], v[230:231]
	v_pk_fma_f32 v[232:233], v[146:147], v[46:47], v[232:233]
	v_pk_fma_f32 v[234:235], v[150:151], v[46:47], v[234:235]
	v_pk_fma_f32 v[236:237], v[154:155], v[46:47], v[236:237]
	v_pk_fma_f32 v[238:239], v[158:159], v[46:47], v[238:239]
	v_pk_fma_f32 v[240:241], v[162:163], v[46:47], v[240:241]
	v_pk_fma_f32 v[242:243], v[166:167], v[46:47], v[242:243]
	v_pk_fma_f32 v[226:227], v[136:137], v[48:49], v[226:227]
	v_pk_fma_f32 v[228:229], v[140:141], v[48:49], v[228:229]
	v_pk_fma_f32 v[230:231], v[144:145], v[48:49], v[230:231]
	v_pk_fma_f32 v[232:233], v[148:149], v[48:49], v[232:233]
	v_pk_fma_f32 v[234:235], v[152:153], v[48:49], v[234:235]
	v_pk_fma_f32 v[236:237], v[156:157], v[48:49], v[236:237]
	v_pk_fma_f32 v[238:239], v[160:161], v[48:49], v[238:239]
	v_pk_fma_f32 v[240:241], v[164:165], v[48:49], v[240:241]
	v_pk_fma_f32 v[242:243], v[168:169], v[48:49], v[242:243]
	ds_read_b128 v[134:137], v1 offset:208
	ds_read_b128 v[138:141], v1 offset:4304
	ds_read_b128 v[142:145], v1 offset:8400
	ds_read_b128 v[146:149], v1 offset:12496
	ds_read_b128 v[150:153], v1 offset:16592
	ds_read_b128 v[154:157], v1 offset:20688
	ds_read_b128 v[158:161], v1 offset:24784
	ds_read_b128 v[162:165], v1 offset:28880
	ds_read_b128 v[166:169], v1 offset:32976
	s_waitcnt lgkmcnt(9)
; #define LAS __attribute__((address_space(3)))
; __device__ __forceinline__ void prologue(const __attribute__((address_space(4))) Args& a, ldsp lds, int gw, int NGW, int wave, int lane, const int tid, const int bid, const int G) {
;     ...
;             for (int q = 0; q < 16; ++q) wv[q] = Wl[(size_t)(k + q) * NMOD];
; #pragma unroll
;             for (int q4 = 0; q4 < 4; ++q4)
; #pragma unroll
;                 for (int j = 0; j < 9; ++j) { const f32x4 s4 = *(const LAS f32x4*)(sc + j * D + k + 4 * q4); acc[j] += s4[0] * wv[4 * q4] + s4[1] * wv[4 * q4 + 1] + s4[2] * wv[4 * q4 + 2] + s4[3] * wv[4 * q4 + 3]; }
	v_pk_fma_f32 v[226:227], v[98:99], v[50:51], v[226:227]
	v_pk_fma_f32 v[228:229], v[102:103], v[50:51], v[228:229]
	v_pk_fma_f32 v[230:231], v[106:107], v[50:51], v[230:231]
	v_pk_fma_f32 v[232:233], v[110:111], v[50:51], v[232:233]
	v_pk_fma_f32 v[234:235], v[114:115], v[50:51], v[234:235]
	v_pk_fma_f32 v[236:237], v[118:119], v[50:51], v[236:237]
	v_pk_fma_f32 v[238:239], v[122:123], v[50:51], v[238:239]
	v_pk_fma_f32 v[240:241], v[126:127], v[50:51], v[240:241]
	v_pk_fma_f32 v[242:243], v[130:131], v[50:51], v[242:243]
	v_pk_fma_f32 v[226:227], v[100:101], v[52:53], v[226:227]
	v_pk_fma_f32 v[228:229], v[104:105], v[52:53], v[228:229]
	v_pk_fma_f32 v[230:231], v[108:109], v[52:53], v[230:231]
	v_pk_fma_f32 v[232:233], v[112:113], v[52:53], v[232:233]
	v_pk_fma_f32 v[234:235], v[116:117], v[52:53], v[234:235]
	v_pk_fma_f32 v[236:237], v[120:121], v[52:53], v[236:237]
	v_pk_fma_f32 v[238:239], v[124:125], v[52:53], v[238:239]
	v_pk_fma_f32 v[240:241], v[128:129], v[52:53], v[240:241]
	v_pk_fma_f32 v[242:243], v[132:133], v[52:53], v[242:243]
	ds_read_b128 v[98:101], v1 offset:224
	ds_read_b128 v[102:105], v1 offset:4320
	ds_read_b128 v[106:109], v1 offset:8416
	ds_read_b128 v[110:113], v1 offset:12512
	ds_read_b128 v[114:117], v1 offset:16608
	ds_read_b128 v[118:121], v1 offset:20704
	ds_read_b128 v[122:125], v1 offset:24800
	ds_read_b128 v[126:129], v1 offset:28896
	ds_read_b128 v[130:133], v1 offset:32992
	s_waitcnt lgkmcnt(9)
	v_pk_fma_f32 v[226:227], v[134:135], v[54:55], v[226:227]
	v_pk_fma_f32 v[228:229], v[138:139], v[54:55], v[228:229]
	v_pk_fma_f32 v[230:231], v[142:143], v[54:55], v[230:231]
	v_pk_fma_f32 v[232:233], v[146:147], v[54:55], v[232:233]
	v_pk_fma_f32 v[234:235], v[150:151], v[54:55], v[234:235]
	v_pk_fma_f32 v[236:237], v[154:155], v[54:55], v[236:237]
	v_pk_fma_f32 v[238:239], v[158:159], v[54:55], v[238:239]
	v_pk_fma_f32 v[240:241], v[162:163], v[54:55], v[240:241]
	v_pk_fma_f32 v[242:243], v[166:167], v[54:55], v[242:243]
	v_pk_fma_f32 v[226:227], v[136:137], v[56:57], v[226:227]
	v_pk_fma_f32 v[228:229], v[140:141], v[56:57], v[228:229]
	v_pk_fma_f32 v[230:231], v[144:145], v[56:57], v[230:231]
	v_pk_fma_f32 v[232:233], v[148:149], v[56:57], v[232:233]
	v_pk_fma_f32 v[234:235], v[152:153], v[56:57], v[234:235]
	v_pk_fma_f32 v[236:237], v[156:157], v[56:57], v[236:237]
	v_pk_fma_f32 v[238:239], v[160:161], v[56:57], v[238:239]
	v_pk_fma_f32 v[240:241], v[164:165], v[56:57], v[240:241]
	v_pk_fma_f32 v[242:243], v[168:169], v[56:57], v[242:243]
	ds_read_b128 v[134:137], v1 offset:240
	ds_read_b128 v[138:141], v1 offset:4336
	ds_read_b128 v[142:145], v1 offset:8432
	ds_read_b128 v[146:149], v1 offset:12528
	ds_read_b128 v[150:153], v1 offset:16624
	ds_read_b128 v[154:157], v1 offset:20720
	ds_read_b128 v[158:161], v1 offset:24816
	ds_read_b128 v[162:165], v1 offset:28912
	ds_read_b128 v[166:169], v1 offset:33008
	s_waitcnt lgkmcnt(9)
	v_pk_fma_f32 v[226:227], v[98:99], v[58:59], v[226:227]
	v_pk_fma_f32 v[228:229], v[102:103], v[58:59], v[228:229]
	v_pk_fma_f32 v[230:231], v[106:107], v[58:59], v[230:231]
	v_pk_fma_f32 v[232:233], v[110:111], v[58:59], v[232:233]
	v_pk_fma_f32 v[234:235], v[114:115], v[58:59], v[234:235]
	v_pk_fma_f32 v[236:237], v[118:119], v[58:59], v[236:237]
	v_pk_fma_f32 v[238:239], v[122:123], v[58:59], v[238:239]
	v_pk_fma_f32 v[240:241], v[126:127], v[58:59], v[240:241]
	v_pk_fma_f32 v[242:243], v[130:131], v[58:59], v[242:243]
	v_pk_fma_f32 v[226:227], v[100:101], v[60:61], v[226:227]
	v_pk_fma_f32 v[228:229], v[104:105], v[60:61], v[228:229]
	v_pk_fma_f32 v[230:231], v[108:109], v[60:61], v[230:231]
	v_pk_fma_f32 v[232:233], v[112:113], v[60:61], v[232:233]
	v_pk_fma_f32 v[234:235], v[116:117], v[60:61], v[234:235]
	v_pk_fma_f32 v[236:237], v[120:121], v[60:61], v[236:237]
	v_pk_fma_f32 v[238:239], v[124:125], v[60:61], v[238:239]
	v_pk_fma_f32 v[240:241], v[128:129], v[60:61], v[240:241]
	v_pk_fma_f32 v[242:243], v[132:133], v[60:61], v[242:243]
	ds_read_b128 v[98:101], v1 offset:256
	ds_read_b128 v[102:105], v1 offset:4352
	ds_read_b128 v[106:109], v1 offset:8448
	ds_read_b128 v[110:113], v1 offset:12544
	ds_read_b128 v[114:117], v1 offset:16640
	ds_read_b128 v[118:121], v1 offset:20736
	ds_read_b128 v[122:125], v1 offset:24832
	ds_read_b128 v[126:129], v1 offset:28928
	ds_read_b128 v[130:133], v1 offset:33024
	s_waitcnt lgkmcnt(9)
; #define LAS __attribute__((address_space(3)))
; __device__ __forceinline__ void prologue(const __attribute__((address_space(4))) Args& a, ldsp lds, int gw, int NGW, int wave, int lane, const int tid, const int bid, const int G) {
;     ...
;         for (int k = wave * 128; k < wave * 128 + 128; k += 16) {
;             float wv[16];
; #pragma unroll
;             for (int q = 0; q < 16; ++q) wv[q] = Wl[(size_t)(k + q) * NMOD];
; #pragma unroll
;             for (int q4 = 0; q4 < 4; ++q4)
; #pragma unroll
;                 for (int j = 0; j < 9; ++j) { const f32x4 s4 = *(const LAS f32x4*)(sc + j * D + k + 4 * q4); acc[j] += s4[0] * wv[4 * q4] + s4[1] * wv[4 * q4 + 1] + s4[2] * wv[4 * q4 + 2] + s4[3] * wv[4 * q4 + 3]; }
	v_pk_fma_f32 v[226:227], v[134:135], v[62:63], v[226:227]
	v_pk_fma_f32 v[228:229], v[138:139], v[62:63], v[228:229]
	v_pk_fma_f32 v[230:231], v[142:143], v[62:63], v[230:231]
	v_pk_fma_f32 v[232:233], v[146:147], v[62:63], v[232:233]
	v_pk_fma_f32 v[234:235], v[150:151], v[62:63], v[234:235]
	v_pk_fma_f32 v[236:237], v[154:155], v[62:63], v[236:237]
	v_pk_fma_f32 v[238:239], v[158:159], v[62:63], v[238:239]
	v_pk_fma_f32 v[240:241], v[162:163], v[62:63], v[240:241]
	v_pk_fma_f32 v[242:243], v[166:167], v[62:63], v[242:243]
	v_pk_fma_f32 v[226:227], v[136:137], v[64:65], v[226:227]
	v_pk_fma_f32 v[228:229], v[140:141], v[64:65], v[228:229]
	v_pk_fma_f32 v[230:231], v[144:145], v[64:65], v[230:231]
	v_pk_fma_f32 v[232:233], v[148:149], v[64:65], v[232:233]
	v_pk_fma_f32 v[234:235], v[152:153], v[64:65], v[234:235]
	v_pk_fma_f32 v[236:237], v[156:157], v[64:65], v[236:237]
	v_pk_fma_f32 v[238:239], v[160:161], v[64:65], v[238:239]
	v_pk_fma_f32 v[240:241], v[164:165], v[64:65], v[240:241]
	v_pk_fma_f32 v[242:243], v[168:169], v[64:65], v[242:243]
	global_load_dword v34, v0, s[22:23] nt
	s_add_u32 s22, s22, 0x6000
	s_addc_u32 s23, s23, 0
	global_load_dword v35, v0, s[22:23] nt
	s_add_u32 s22, s22, 0x6000
	s_addc_u32 s23, s23, 0
	global_load_dword v36, v0, s[22:23] nt
	s_add_u32 s22, s22, 0x6000
	s_addc_u32 s23, s23, 0
	global_load_dword v37, v0, s[22:23] nt
	s_add_u32 s22, s22, 0x6000
	s_addc_u32 s23, s23, 0
	global_load_dword v38, v0, s[22:23] nt
	s_add_u32 s22, s22, 0x6000
	s_addc_u32 s23, s23, 0
	global_load_dword v39, v0, s[22:23] nt
	s_add_u32 s22, s22, 0x6000
	s_addc_u32 s23, s23, 0
	global_load_dword v40, v0, s[22:23] nt
	s_add_u32 s22, s22, 0x6000
	s_addc_u32 s23, s23, 0
	global_load_dword v41, v0, s[22:23] nt
	s_add_u32 s22, s22, 0x6000
	s_addc_u32 s23, s23, 0
	global_load_dword v42, v0, s[22:23] nt
	s_add_u32 s22, s22, 0x6000
	s_addc_u32 s23, s23, 0
	global_load_dword v43, v0, s[22:23] nt
	s_add_u32 s22, s22, 0x6000
	s_addc_u32 s23, s23, 0
	global_load_dword v44, v0, s[22:23] nt
	s_add_u32 s22, s22, 0x6000
	s_addc_u32 s23, s23, 0
	global_load_dword v45, v0, s[22:23] nt
	s_add_u32 s22, s22, 0x6000
	s_addc_u32 s23, s23, 0
	global_load_dword v46, v0, s[22:23] nt
	s_add_u32 s22, s22, 0x6000
	s_addc_u32 s23, s23, 0
	global_load_dword v47, v0, s[22:23] nt
	s_add_u32 s22, s22, 0x6000
	s_addc_u32 s23, s23, 0
	global_load_dword v48, v0, s[22:23] nt
	s_add_u32 s22, s22, 0x6000
	s_addc_u32 s23, s23, 0
	global_load_dword v49, v0, s[22:23] nt
	s_add_u32 s22, s22, 0x6000
	s_addc_u32 s23, s23, 0
	global_load_dword v50, v0, s[22:23] nt
	s_add_u32 s22, s22, 0x6000
	s_addc_u32 s23, s23, 0
	global_load_dword v51, v0, s[22:23] nt
	s_add_u32 s22, s22, 0x6000
	s_addc_u32 s23, s23, 0
	global_load_dword v52, v0, s[22:23] nt
	s_add_u32 s22, s22, 0x6000
	s_addc_u32 s23, s23, 0
	global_load_dword v53, v0, s[22:23] nt
	s_add_u32 s22, s22, 0x6000
	s_addc_u32 s23, s23, 0
	global_load_dword v54, v0, s[22:23] nt
	s_add_u32 s22, s22, 0x6000
	s_addc_u32 s23, s23, 0
	global_load_dword v55, v0, s[22:23] nt
	s_add_u32 s22, s22, 0x6000
	s_addc_u32 s23, s23, 0
	global_load_dword v56, v0, s[22:23] nt
	s_add_u32 s22, s22, 0x6000
	s_addc_u32 s23, s23, 0
	global_load_dword v57, v0, s[22:23] nt
	s_add_u32 s22, s22, 0x6000
	s_addc_u32 s23, s23, 0
	global_load_dword v58, v0, s[22:23] nt
	s_add_u32 s22, s22, 0x6000
	s_addc_u32 s23, s23, 0
	global_load_dword v59, v0, s[22:23] nt
	s_add_u32 s22, s22, 0x6000
	s_addc_u32 s23, s23, 0
	global_load_dword v60, v0, s[22:23] nt
	s_add_u32 s22, s22, 0x6000
	s_addc_u32 s23, s23, 0
	global_load_dword v61, v0, s[22:23] nt
	s_add_u32 s22, s22, 0x6000
	s_addc_u32 s23, s23, 0
	global_load_dword v62, v0, s[22:23] nt
	s_add_u32 s22, s22, 0x6000
	s_addc_u32 s23, s23, 0
	global_load_dword v63, v0, s[22:23] nt
	s_add_u32 s22, s22, 0x6000
	s_addc_u32 s23, s23, 0
	global_load_dword v64, v0, s[22:23] nt
	s_add_u32 s22, s22, 0x6000
	s_addc_u32 s23, s23, 0
	global_load_dword v65, v0, s[22:23] nt
	s_add_u32 s22, s22, 0x6000
	s_addc_u32 s23, s23, 0
	s_waitcnt vmcnt(32)
	ds_read_b128 v[134:137], v1 offset:272
	ds_read_b128 v[138:141], v1 offset:4368
	ds_read_b128 v[142:145], v1 offset:8464
	ds_read_b128 v[146:149], v1 offset:12560
	ds_read_b128 v[150:153], v1 offset:16656
	ds_read_b128 v[154:157], v1 offset:20752
	ds_read_b128 v[158:161], v1 offset:24848
	ds_read_b128 v[162:165], v1 offset:28944
	ds_read_b128 v[166:169], v1 offset:33040
	s_waitcnt lgkmcnt(9)
	v_pk_fma_f32 v[226:227], v[98:99], v[2:3], v[226:227]
	v_pk_fma_f32 v[228:229], v[102:103], v[2:3], v[228:229]
	v_pk_fma_f32 v[230:231], v[106:107], v[2:3], v[230:231]
	v_pk_fma_f32 v[232:233], v[110:111], v[2:3], v[232:233]
	v_pk_fma_f32 v[234:235], v[114:115], v[2:3], v[234:235]
	v_pk_fma_f32 v[236:237], v[118:119], v[2:3], v[236:237]
	v_pk_fma_f32 v[238:239], v[122:123], v[2:3], v[238:239]
	v_pk_fma_f32 v[240:241], v[126:127], v[2:3], v[240:241]
	v_pk_fma_f32 v[242:243], v[130:131], v[2:3], v[242:243]
	v_pk_fma_f32 v[226:227], v[100:101], v[4:5], v[226:227]
	v_pk_fma_f32 v[228:229], v[104:105], v[4:5], v[228:229]
	v_pk_fma_f32 v[230:231], v[108:109], v[4:5], v[230:231]
	v_pk_fma_f32 v[232:233], v[112:113], v[4:5], v[232:233]
	v_pk_fma_f32 v[234:235], v[116:117], v[4:5], v[234:235]
	v_pk_fma_f32 v[236:237], v[120:121], v[4:5], v[236:237]
	v_pk_fma_f32 v[238:239], v[124:125], v[4:5], v[238:239]
	v_pk_fma_f32 v[240:241], v[128:129], v[4:5], v[240:241]
	v_pk_fma_f32 v[242:243], v[132:133], v[4:5], v[242:243]
	ds_read_b128 v[98:101], v1 offset:288
	ds_read_b128 v[102:105], v1 offset:4384
	ds_read_b128 v[106:109], v1 offset:8480
	ds_read_b128 v[110:113], v1 offset:12576
	ds_read_b128 v[114:117], v1 offset:16672
	ds_read_b128 v[118:121], v1 offset:20768
	ds_read_b128 v[122:125], v1 offset:24864
	ds_read_b128 v[126:129], v1 offset:28960
	ds_read_b128 v[130:133], v1 offset:33056
	s_waitcnt lgkmcnt(9)
; #define LAS __attribute__((address_space(3)))
; __device__ __forceinline__ void prologue(const __attribute__((address_space(4))) Args& a, ldsp lds, int gw, int NGW, int wave, int lane, const int tid, const int bid, const int G) {
;     ...
;             for (int q = 0; q < 16; ++q) wv[q] = Wl[(size_t)(k + q) * NMOD];
; #pragma unroll
;             for (int q4 = 0; q4 < 4; ++q4)
; #pragma unroll
;                 for (int j = 0; j < 9; ++j) { const f32x4 s4 = *(const LAS f32x4*)(sc + j * D + k + 4 * q4); acc[j] += s4[0] * wv[4 * q4] + s4[1] * wv[4 * q4 + 1] + s4[2] * wv[4 * q4 + 2] + s4[3] * wv[4 * q4 + 3]; }
	v_pk_fma_f32 v[226:227], v[134:135], v[6:7], v[226:227]
	v_pk_fma_f32 v[228:229], v[138:139], v[6:7], v[228:229]
	v_pk_fma_f32 v[230:231], v[142:143], v[6:7], v[230:231]
	v_pk_fma_f32 v[232:233], v[146:147], v[6:7], v[232:233]
	v_pk_fma_f32 v[234:235], v[150:151], v[6:7], v[234:235]
	v_pk_fma_f32 v[236:237], v[154:155], v[6:7], v[236:237]
	v_pk_fma_f32 v[238:239], v[158:159], v[6:7], v[238:239]
	v_pk_fma_f32 v[240:241], v[162:163], v[6:7], v[240:241]
	v_pk_fma_f32 v[242:243], v[166:167], v[6:7], v[242:243]
	v_pk_fma_f32 v[226:227], v[136:137], v[8:9], v[226:227]
	v_pk_fma_f32 v[228:229], v[140:141], v[8:9], v[228:229]
	v_pk_fma_f32 v[230:231], v[144:145], v[8:9], v[230:231]
	v_pk_fma_f32 v[232:233], v[148:149], v[8:9], v[232:233]
	v_pk_fma_f32 v[234:235], v[152:153], v[8:9], v[234:235]
	v_pk_fma_f32 v[236:237], v[156:157], v[8:9], v[236:237]
	v_pk_fma_f32 v[238:239], v[160:161], v[8:9], v[238:239]
	v_pk_fma_f32 v[240:241], v[164:165], v[8:9], v[240:241]
	v_pk_fma_f32 v[242:243], v[168:169], v[8:9], v[242:243]
	ds_read_b128 v[134:137], v1 offset:304
	ds_read_b128 v[138:141], v1 offset:4400
	ds_read_b128 v[142:145], v1 offset:8496
	ds_read_b128 v[146:149], v1 offset:12592
	ds_read_b128 v[150:153], v1 offset:16688
	ds_read_b128 v[154:157], v1 offset:20784
	ds_read_b128 v[158:161], v1 offset:24880
	ds_read_b128 v[162:165], v1 offset:28976
	ds_read_b128 v[166:169], v1 offset:33072
	s_waitcnt lgkmcnt(9)
	v_pk_fma_f32 v[226:227], v[98:99], v[10:11], v[226:227]
	v_pk_fma_f32 v[228:229], v[102:103], v[10:11], v[228:229]
	v_pk_fma_f32 v[230:231], v[106:107], v[10:11], v[230:231]
	v_pk_fma_f32 v[232:233], v[110:111], v[10:11], v[232:233]
	v_pk_fma_f32 v[234:235], v[114:115], v[10:11], v[234:235]
	v_pk_fma_f32 v[236:237], v[118:119], v[10:11], v[236:237]
	v_pk_fma_f32 v[238:239], v[122:123], v[10:11], v[238:239]
	v_pk_fma_f32 v[240:241], v[126:127], v[10:11], v[240:241]
	v_pk_fma_f32 v[242:243], v[130:131], v[10:11], v[242:243]
	v_pk_fma_f32 v[226:227], v[100:101], v[12:13], v[226:227]
	v_pk_fma_f32 v[228:229], v[104:105], v[12:13], v[228:229]
	v_pk_fma_f32 v[230:231], v[108:109], v[12:13], v[230:231]
	v_pk_fma_f32 v[232:233], v[112:113], v[12:13], v[232:233]
	v_pk_fma_f32 v[234:235], v[116:117], v[12:13], v[234:235]
	v_pk_fma_f32 v[236:237], v[120:121], v[12:13], v[236:237]
	v_pk_fma_f32 v[238:239], v[124:125], v[12:13], v[238:239]
	v_pk_fma_f32 v[240:241], v[128:129], v[12:13], v[240:241]
	v_pk_fma_f32 v[242:243], v[132:133], v[12:13], v[242:243]
	ds_read_b128 v[98:101], v1 offset:320
	ds_read_b128 v[102:105], v1 offset:4416
	ds_read_b128 v[106:109], v1 offset:8512
	ds_read_b128 v[110:113], v1 offset:12608
	ds_read_b128 v[114:117], v1 offset:16704
	ds_read_b128 v[118:121], v1 offset:20800
	ds_read_b128 v[122:125], v1 offset:24896
	ds_read_b128 v[126:129], v1 offset:28992
	ds_read_b128 v[130:133], v1 offset:33088
	s_waitcnt lgkmcnt(9)
	v_pk_fma_f32 v[226:227], v[134:135], v[14:15], v[226:227]
	v_pk_fma_f32 v[228:229], v[138:139], v[14:15], v[228:229]
	v_pk_fma_f32 v[230:231], v[142:143], v[14:15], v[230:231]
	v_pk_fma_f32 v[232:233], v[146:147], v[14:15], v[232:233]
	v_pk_fma_f32 v[234:235], v[150:151], v[14:15], v[234:235]
	v_pk_fma_f32 v[236:237], v[154:155], v[14:15], v[236:237]
	v_pk_fma_f32 v[238:239], v[158:159], v[14:15], v[238:239]
	v_pk_fma_f32 v[240:241], v[162:163], v[14:15], v[240:241]
	v_pk_fma_f32 v[242:243], v[166:167], v[14:15], v[242:243]
	v_pk_fma_f32 v[226:227], v[136:137], v[16:17], v[226:227]
	v_pk_fma_f32 v[228:229], v[140:141], v[16:17], v[228:229]
	v_pk_fma_f32 v[230:231], v[144:145], v[16:17], v[230:231]
	v_pk_fma_f32 v[232:233], v[148:149], v[16:17], v[232:233]
	v_pk_fma_f32 v[234:235], v[152:153], v[16:17], v[234:235]
	v_pk_fma_f32 v[236:237], v[156:157], v[16:17], v[236:237]
	v_pk_fma_f32 v[238:239], v[160:161], v[16:17], v[238:239]
	v_pk_fma_f32 v[240:241], v[164:165], v[16:17], v[240:241]
	v_pk_fma_f32 v[242:243], v[168:169], v[16:17], v[242:243]
	ds_read_b128 v[134:137], v1 offset:336
	ds_read_b128 v[138:141], v1 offset:4432
	ds_read_b128 v[142:145], v1 offset:8528
	ds_read_b128 v[146:149], v1 offset:12624
	ds_read_b128 v[150:153], v1 offset:16720
	ds_read_b128 v[154:157], v1 offset:20816
	ds_read_b128 v[158:161], v1 offset:24912
	ds_read_b128 v[162:165], v1 offset:29008
	ds_read_b128 v[166:169], v1 offset:33104
	s_waitcnt lgkmcnt(9)
	v_pk_fma_f32 v[226:227], v[98:99], v[18:19], v[226:227]
	v_pk_fma_f32 v[228:229], v[102:103], v[18:19], v[228:229]
	v_pk_fma_f32 v[230:231], v[106:107], v[18:19], v[230:231]
	v_pk_fma_f32 v[232:233], v[110:111], v[18:19], v[232:233]
	v_pk_fma_f32 v[234:235], v[114:115], v[18:19], v[234:235]
	v_pk_fma_f32 v[236:237], v[118:119], v[18:19], v[236:237]
	v_pk_fma_f32 v[238:239], v[122:123], v[18:19], v[238:239]
	v_pk_fma_f32 v[240:241], v[126:127], v[18:19], v[240:241]
	v_pk_fma_f32 v[242:243], v[130:131], v[18:19], v[242:243]
	v_pk_fma_f32 v[226:227], v[100:101], v[20:21], v[226:227]
	v_pk_fma_f32 v[228:229], v[104:105], v[20:21], v[228:229]
	v_pk_fma_f32 v[230:231], v[108:109], v[20:21], v[230:231]
	v_pk_fma_f32 v[232:233], v[112:113], v[20:21], v[232:233]
	v_pk_fma_f32 v[234:235], v[116:117], v[20:21], v[234:235]
	v_pk_fma_f32 v[236:237], v[120:121], v[20:21], v[236:237]
	v_pk_fma_f32 v[238:239], v[124:125], v[20:21], v[238:239]
	v_pk_fma_f32 v[240:241], v[128:129], v[20:21], v[240:241]
	v_pk_fma_f32 v[242:243], v[132:133], v[20:21], v[242:243]
	ds_read_b128 v[98:101], v1 offset:352
	ds_read_b128 v[102:105], v1 offset:4448
	ds_read_b128 v[106:109], v1 offset:8544
	ds_read_b128 v[110:113], v1 offset:12640
	ds_read_b128 v[114:117], v1 offset:16736
	ds_read_b128 v[118:121], v1 offset:20832
	ds_read_b128 v[122:125], v1 offset:24928
	ds_read_b128 v[126:129], v1 offset:29024
	ds_read_b128 v[130:133], v1 offset:33120
	s_waitcnt lgkmcnt(9)
; #define LAS __attribute__((address_space(3)))
; __device__ __forceinline__ void prologue(const __attribute__((address_space(4))) Args& a, ldsp lds, int gw, int NGW, int wave, int lane, const int tid, const int bid, const int G) {
;     ...
;             for (int q = 0; q < 16; ++q) wv[q] = Wl[(size_t)(k + q) * NMOD];
; #pragma unroll
;             for (int q4 = 0; q4 < 4; ++q4)
; #pragma unroll
;                 for (int j = 0; j < 9; ++j) { const f32x4 s4 = *(const LAS f32x4*)(sc + j * D + k + 4 * q4); acc[j] += s4[0] * wv[4 * q4] + s4[1] * wv[4 * q4 + 1] + s4[2] * wv[4 * q4 + 2] + s4[3] * wv[4 * q4 + 3]; }
	v_pk_fma_f32 v[226:227], v[134:135], v[22:23], v[226:227]
	v_pk_fma_f32 v[228:229], v[138:139], v[22:23], v[228:229]
	v_pk_fma_f32 v[230:231], v[142:143], v[22:23], v[230:231]
	v_pk_fma_f32 v[232:233], v[146:147], v[22:23], v[232:233]
	v_pk_fma_f32 v[234:235], v[150:151], v[22:23], v[234:235]
	v_pk_fma_f32 v[236:237], v[154:155], v[22:23], v[236:237]
	v_pk_fma_f32 v[238:239], v[158:159], v[22:23], v[238:239]
	v_pk_fma_f32 v[240:241], v[162:163], v[22:23], v[240:241]
	v_pk_fma_f32 v[242:243], v[166:167], v[22:23], v[242:243]
	v_pk_fma_f32 v[226:227], v[136:137], v[24:25], v[226:227]
	v_pk_fma_f32 v[228:229], v[140:141], v[24:25], v[228:229]
	v_pk_fma_f32 v[230:231], v[144:145], v[24:25], v[230:231]
	v_pk_fma_f32 v[232:233], v[148:149], v[24:25], v[232:233]
	v_pk_fma_f32 v[234:235], v[152:153], v[24:25], v[234:235]
	v_pk_fma_f32 v[236:237], v[156:157], v[24:25], v[236:237]
	v_pk_fma_f32 v[238:239], v[160:161], v[24:25], v[238:239]
	v_pk_fma_f32 v[240:241], v[164:165], v[24:25], v[240:241]
	v_pk_fma_f32 v[242:243], v[168:169], v[24:25], v[242:243]
	ds_read_b128 v[134:137], v1 offset:368
	ds_read_b128 v[138:141], v1 offset:4464
	ds_read_b128 v[142:145], v1 offset:8560
	ds_read_b128 v[146:149], v1 offset:12656
	ds_read_b128 v[150:153], v1 offset:16752
	ds_read_b128 v[154:157], v1 offset:20848
	ds_read_b128 v[158:161], v1 offset:24944
	ds_read_b128 v[162:165], v1 offset:29040
	ds_read_b128 v[166:169], v1 offset:33136
	s_waitcnt lgkmcnt(9)
	v_pk_fma_f32 v[226:227], v[98:99], v[26:27], v[226:227]
	v_pk_fma_f32 v[228:229], v[102:103], v[26:27], v[228:229]
	v_pk_fma_f32 v[230:231], v[106:107], v[26:27], v[230:231]
	v_pk_fma_f32 v[232:233], v[110:111], v[26:27], v[232:233]
	v_pk_fma_f32 v[234:235], v[114:115], v[26:27], v[234:235]
	v_pk_fma_f32 v[236:237], v[118:119], v[26:27], v[236:237]
	v_pk_fma_f32 v[238:239], v[122:123], v[26:27], v[238:239]
	v_pk_fma_f32 v[240:241], v[126:127], v[26:27], v[240:241]
	v_pk_fma_f32 v[242:243], v[130:131], v[26:27], v[242:243]
	v_pk_fma_f32 v[226:227], v[100:101], v[28:29], v[226:227]
	v_pk_fma_f32 v[228:229], v[104:105], v[28:29], v[228:229]
	v_pk_fma_f32 v[230:231], v[108:109], v[28:29], v[230:231]
	v_pk_fma_f32 v[232:233], v[112:113], v[28:29], v[232:233]
	v_pk_fma_f32 v[234:235], v[116:117], v[28:29], v[234:235]
	v_pk_fma_f32 v[236:237], v[120:121], v[28:29], v[236:237]
	v_pk_fma_f32 v[238:239], v[124:125], v[28:29], v[238:239]
	v_pk_fma_f32 v[240:241], v[128:129], v[28:29], v[240:241]
	v_pk_fma_f32 v[242:243], v[132:133], v[28:29], v[242:243]
	ds_read_b128 v[98:101], v1 offset:384
	ds_read_b128 v[102:105], v1 offset:4480
	ds_read_b128 v[106:109], v1 offset:8576
	ds_read_b128 v[110:113], v1 offset:12672
	ds_read_b128 v[114:117], v1 offset:16768
	ds_read_b128 v[118:121], v1 offset:20864
	ds_read_b128 v[122:125], v1 offset:24960
	ds_read_b128 v[126:129], v1 offset:29056
	ds_read_b128 v[130:133], v1 offset:33152
	s_waitcnt lgkmcnt(9)
	v_pk_fma_f32 v[226:227], v[134:135], v[30:31], v[226:227]
	v_pk_fma_f32 v[228:229], v[138:139], v[30:31], v[228:229]
	v_pk_fma_f32 v[230:231], v[142:143], v[30:31], v[230:231]
	v_pk_fma_f32 v[232:233], v[146:147], v[30:31], v[232:233]
	v_pk_fma_f32 v[234:235], v[150:151], v[30:31], v[234:235]
	v_pk_fma_f32 v[236:237], v[154:155], v[30:31], v[236:237]
	v_pk_fma_f32 v[238:239], v[158:159], v[30:31], v[238:239]
	v_pk_fma_f32 v[240:241], v[162:163], v[30:31], v[240:241]
	v_pk_fma_f32 v[242:243], v[166:167], v[30:31], v[242:243]
	v_pk_fma_f32 v[226:227], v[136:137], v[32:33], v[226:227]
	v_pk_fma_f32 v[228:229], v[140:141], v[32:33], v[228:229]
	v_pk_fma_f32 v[230:231], v[144:145], v[32:33], v[230:231]
	v_pk_fma_f32 v[232:233], v[148:149], v[32:33], v[232:233]
	v_pk_fma_f32 v[234:235], v[152:153], v[32:33], v[234:235]
	v_pk_fma_f32 v[236:237], v[156:157], v[32:33], v[236:237]
	v_pk_fma_f32 v[238:239], v[160:161], v[32:33], v[238:239]
	v_pk_fma_f32 v[240:241], v[164:165], v[32:33], v[240:241]
	v_pk_fma_f32 v[242:243], v[168:169], v[32:33], v[242:243]
	s_waitcnt vmcnt(0)
	ds_read_b128 v[134:137], v1 offset:400
	ds_read_b128 v[138:141], v1 offset:4496
	ds_read_b128 v[142:145], v1 offset:8592
	ds_read_b128 v[146:149], v1 offset:12688
	ds_read_b128 v[150:153], v1 offset:16784
	ds_read_b128 v[154:157], v1 offset:20880
	ds_read_b128 v[158:161], v1 offset:24976
	ds_read_b128 v[162:165], v1 offset:29072
	ds_read_b128 v[166:169], v1 offset:33168
	s_waitcnt lgkmcnt(9)
	v_pk_fma_f32 v[226:227], v[98:99], v[34:35], v[226:227]
	v_pk_fma_f32 v[228:229], v[102:103], v[34:35], v[228:229]
	v_pk_fma_f32 v[230:231], v[106:107], v[34:35], v[230:231]
	v_pk_fma_f32 v[232:233], v[110:111], v[34:35], v[232:233]
	v_pk_fma_f32 v[234:235], v[114:115], v[34:35], v[234:235]
	v_pk_fma_f32 v[236:237], v[118:119], v[34:35], v[236:237]
	v_pk_fma_f32 v[238:239], v[122:123], v[34:35], v[238:239]
	v_pk_fma_f32 v[240:241], v[126:127], v[34:35], v[240:241]
	v_pk_fma_f32 v[242:243], v[130:131], v[34:35], v[242:243]
	v_pk_fma_f32 v[226:227], v[100:101], v[36:37], v[226:227]
	v_pk_fma_f32 v[228:229], v[104:105], v[36:37], v[228:229]
	v_pk_fma_f32 v[230:231], v[108:109], v[36:37], v[230:231]
	v_pk_fma_f32 v[232:233], v[112:113], v[36:37], v[232:233]
	v_pk_fma_f32 v[234:235], v[116:117], v[36:37], v[234:235]
	v_pk_fma_f32 v[236:237], v[120:121], v[36:37], v[236:237]
	v_pk_fma_f32 v[238:239], v[124:125], v[36:37], v[238:239]
	v_pk_fma_f32 v[240:241], v[128:129], v[36:37], v[240:241]
	v_pk_fma_f32 v[242:243], v[132:133], v[36:37], v[242:243]
	ds_read_b128 v[98:101], v1 offset:416
	ds_read_b128 v[102:105], v1 offset:4512
	ds_read_b128 v[106:109], v1 offset:8608
	ds_read_b128 v[110:113], v1 offset:12704
	ds_read_b128 v[114:117], v1 offset:16800
	ds_read_b128 v[118:121], v1 offset:20896
	ds_read_b128 v[122:125], v1 offset:24992
	ds_read_b128 v[126:129], v1 offset:29088
	ds_read_b128 v[130:133], v1 offset:33184
	s_waitcnt lgkmcnt(9)
; #define LAS __attribute__((address_space(3)))
; __device__ __forceinline__ void prologue(const __attribute__((address_space(4))) Args& a, ldsp lds, int gw, int NGW, int wave, int lane, const int tid, const int bid, const int G) {
;     ...
;             for (int q = 0; q < 16; ++q) wv[q] = Wl[(size_t)(k + q) * NMOD];
; #pragma unroll
;             for (int q4 = 0; q4 < 4; ++q4)
; #pragma unroll
;                 for (int j = 0; j < 9; ++j) { const f32x4 s4 = *(const LAS f32x4*)(sc + j * D + k + 4 * q4); acc[j] += s4[0] * wv[4 * q4] + s4[1] * wv[4 * q4 + 1] + s4[2] * wv[4 * q4 + 2] + s4[3] * wv[4 * q4 + 3]; }
	v_pk_fma_f32 v[226:227], v[134:135], v[38:39], v[226:227]
	v_pk_fma_f32 v[228:229], v[138:139], v[38:39], v[228:229]
	v_pk_fma_f32 v[230:231], v[142:143], v[38:39], v[230:231]
	v_pk_fma_f32 v[232:233], v[146:147], v[38:39], v[232:233]
	v_pk_fma_f32 v[234:235], v[150:151], v[38:39], v[234:235]
	v_pk_fma_f32 v[236:237], v[154:155], v[38:39], v[236:237]
	v_pk_fma_f32 v[238:239], v[158:159], v[38:39], v[238:239]
	v_pk_fma_f32 v[240:241], v[162:163], v[38:39], v[240:241]
	v_pk_fma_f32 v[242:243], v[166:167], v[38:39], v[242:243]
	v_pk_fma_f32 v[226:227], v[136:137], v[40:41], v[226:227]
	v_pk_fma_f32 v[228:229], v[140:141], v[40:41], v[228:229]
	v_pk_fma_f32 v[230:231], v[144:145], v[40:41], v[230:231]
	v_pk_fma_f32 v[232:233], v[148:149], v[40:41], v[232:233]
	v_pk_fma_f32 v[234:235], v[152:153], v[40:41], v[234:235]
	v_pk_fma_f32 v[236:237], v[156:157], v[40:41], v[236:237]
	v_pk_fma_f32 v[238:239], v[160:161], v[40:41], v[238:239]
	v_pk_fma_f32 v[240:241], v[164:165], v[40:41], v[240:241]
	v_pk_fma_f32 v[242:243], v[168:169], v[40:41], v[242:243]
	ds_read_b128 v[134:137], v1 offset:432
	ds_read_b128 v[138:141], v1 offset:4528
	ds_read_b128 v[142:145], v1 offset:8624
	ds_read_b128 v[146:149], v1 offset:12720
	ds_read_b128 v[150:153], v1 offset:16816
	ds_read_b128 v[154:157], v1 offset:20912
	ds_read_b128 v[158:161], v1 offset:25008
	ds_read_b128 v[162:165], v1 offset:29104
	ds_read_b128 v[166:169], v1 offset:33200
	s_waitcnt lgkmcnt(9)
	v_pk_fma_f32 v[226:227], v[98:99], v[42:43], v[226:227]
	v_pk_fma_f32 v[228:229], v[102:103], v[42:43], v[228:229]
	v_pk_fma_f32 v[230:231], v[106:107], v[42:43], v[230:231]
	v_pk_fma_f32 v[232:233], v[110:111], v[42:43], v[232:233]
	v_pk_fma_f32 v[234:235], v[114:115], v[42:43], v[234:235]
	v_pk_fma_f32 v[236:237], v[118:119], v[42:43], v[236:237]
	v_pk_fma_f32 v[238:239], v[122:123], v[42:43], v[238:239]
	v_pk_fma_f32 v[240:241], v[126:127], v[42:43], v[240:241]
	v_pk_fma_f32 v[242:243], v[130:131], v[42:43], v[242:243]
	v_pk_fma_f32 v[226:227], v[100:101], v[44:45], v[226:227]
	v_pk_fma_f32 v[228:229], v[104:105], v[44:45], v[228:229]
	v_pk_fma_f32 v[230:231], v[108:109], v[44:45], v[230:231]
	v_pk_fma_f32 v[232:233], v[112:113], v[44:45], v[232:233]
	v_pk_fma_f32 v[234:235], v[116:117], v[44:45], v[234:235]
	v_pk_fma_f32 v[236:237], v[120:121], v[44:45], v[236:237]
	v_pk_fma_f32 v[238:239], v[124:125], v[44:45], v[238:239]
	v_pk_fma_f32 v[240:241], v[128:129], v[44:45], v[240:241]
	v_pk_fma_f32 v[242:243], v[132:133], v[44:45], v[242:243]
	ds_read_b128 v[98:101], v1 offset:448
	ds_read_b128 v[102:105], v1 offset:4544
	ds_read_b128 v[106:109], v1 offset:8640
	ds_read_b128 v[110:113], v1 offset:12736
	ds_read_b128 v[114:117], v1 offset:16832
	ds_read_b128 v[118:121], v1 offset:20928
	ds_read_b128 v[122:125], v1 offset:25024
	ds_read_b128 v[126:129], v1 offset:29120
	ds_read_b128 v[130:133], v1 offset:33216
	s_waitcnt lgkmcnt(9)
	v_pk_fma_f32 v[226:227], v[134:135], v[46:47], v[226:227]
	v_pk_fma_f32 v[228:229], v[138:139], v[46:47], v[228:229]
	v_pk_fma_f32 v[230:231], v[142:143], v[46:47], v[230:231]
	v_pk_fma_f32 v[232:233], v[146:147], v[46:47], v[232:233]
	v_pk_fma_f32 v[234:235], v[150:151], v[46:47], v[234:235]
	v_pk_fma_f32 v[236:237], v[154:155], v[46:47], v[236:237]
	v_pk_fma_f32 v[238:239], v[158:159], v[46:47], v[238:239]
	v_pk_fma_f32 v[240:241], v[162:163], v[46:47], v[240:241]
	v_pk_fma_f32 v[242:243], v[166:167], v[46:47], v[242:243]
	v_pk_fma_f32 v[226:227], v[136:137], v[48:49], v[226:227]
	v_pk_fma_f32 v[228:229], v[140:141], v[48:49], v[228:229]
	v_pk_fma_f32 v[230:231], v[144:145], v[48:49], v[230:231]
	v_pk_fma_f32 v[232:233], v[148:149], v[48:49], v[232:233]
	v_pk_fma_f32 v[234:235], v[152:153], v[48:49], v[234:235]
	v_pk_fma_f32 v[236:237], v[156:157], v[48:49], v[236:237]
	v_pk_fma_f32 v[238:239], v[160:161], v[48:49], v[238:239]
	v_pk_fma_f32 v[240:241], v[164:165], v[48:49], v[240:241]
	v_pk_fma_f32 v[242:243], v[168:169], v[48:49], v[242:243]
	ds_read_b128 v[134:137], v1 offset:464
	ds_read_b128 v[138:141], v1 offset:4560
	ds_read_b128 v[142:145], v1 offset:8656
	ds_read_b128 v[146:149], v1 offset:12752
	ds_read_b128 v[150:153], v1 offset:16848
	ds_read_b128 v[154:157], v1 offset:20944
	ds_read_b128 v[158:161], v1 offset:25040
	ds_read_b128 v[162:165], v1 offset:29136
	ds_read_b128 v[166:169], v1 offset:33232
	s_waitcnt lgkmcnt(9)
	v_pk_fma_f32 v[226:227], v[98:99], v[50:51], v[226:227]
	v_pk_fma_f32 v[228:229], v[102:103], v[50:51], v[228:229]
	v_pk_fma_f32 v[230:231], v[106:107], v[50:51], v[230:231]
	v_pk_fma_f32 v[232:233], v[110:111], v[50:51], v[232:233]
	v_pk_fma_f32 v[234:235], v[114:115], v[50:51], v[234:235]
	v_pk_fma_f32 v[236:237], v[118:119], v[50:51], v[236:237]
	v_pk_fma_f32 v[238:239], v[122:123], v[50:51], v[238:239]
	v_pk_fma_f32 v[240:241], v[126:127], v[50:51], v[240:241]
	v_pk_fma_f32 v[242:243], v[130:131], v[50:51], v[242:243]
	v_pk_fma_f32 v[226:227], v[100:101], v[52:53], v[226:227]
	v_pk_fma_f32 v[228:229], v[104:105], v[52:53], v[228:229]
	v_pk_fma_f32 v[230:231], v[108:109], v[52:53], v[230:231]
	v_pk_fma_f32 v[232:233], v[112:113], v[52:53], v[232:233]
	v_pk_fma_f32 v[234:235], v[116:117], v[52:53], v[234:235]
	v_pk_fma_f32 v[236:237], v[120:121], v[52:53], v[236:237]
	v_pk_fma_f32 v[238:239], v[124:125], v[52:53], v[238:239]
	v_pk_fma_f32 v[240:241], v[128:129], v[52:53], v[240:241]
	v_pk_fma_f32 v[242:243], v[132:133], v[52:53], v[242:243]
	ds_read_b128 v[98:101], v1 offset:480
	ds_read_b128 v[102:105], v1 offset:4576
	ds_read_b128 v[106:109], v1 offset:8672
	ds_read_b128 v[110:113], v1 offset:12768
	ds_read_b128 v[114:117], v1 offset:16864
	ds_read_b128 v[118:121], v1 offset:20960
	ds_read_b128 v[122:125], v1 offset:25056
	ds_read_b128 v[126:129], v1 offset:29152
	ds_read_b128 v[130:133], v1 offset:33248
	s_waitcnt lgkmcnt(9)
; #define LAS __attribute__((address_space(3)))
; __device__ __forceinline__ void prologue(const __attribute__((address_space(4))) Args& a, ldsp lds, int gw, int NGW, int wave, int lane, const int tid, const int bid, const int G) {
;     ...
;                 for (int j = 0; j < 9; ++j) { const f32x4 s4 = *(const LAS f32x4*)(sc + j * D + k + 4 * q4); acc[j] += s4[0] * wv[4 * q4] + s4[1] * wv[4 * q4 + 1] + s4[2] * wv[4 * q4 + 2] + s4[3] * wv[4 * q4 + 3]; }
;         }
; #pragma unroll
;         for (int j = 0; j < 9; ++j) red[(wave * 9 + j) * 64 + lane] = acc[j];
;         __syncthreads();
;         for (int i = tid; i < 9 * 64; i += 512) { const int j = i >> 6, cc = i & 63; float s = a.ada_b[layer * NMOD + col0 + cc];
	v_pk_fma_f32 v[226:227], v[134:135], v[54:55], v[226:227]
	v_pk_fma_f32 v[228:229], v[138:139], v[54:55], v[228:229]
	v_pk_fma_f32 v[230:231], v[142:143], v[54:55], v[230:231]
	v_pk_fma_f32 v[232:233], v[146:147], v[54:55], v[232:233]
	v_pk_fma_f32 v[234:235], v[150:151], v[54:55], v[234:235]
	v_pk_fma_f32 v[236:237], v[154:155], v[54:55], v[236:237]
	v_pk_fma_f32 v[238:239], v[158:159], v[54:55], v[238:239]
	v_pk_fma_f32 v[240:241], v[162:163], v[54:55], v[240:241]
	v_pk_fma_f32 v[242:243], v[166:167], v[54:55], v[242:243]
	v_pk_fma_f32 v[226:227], v[136:137], v[56:57], v[226:227]
	v_pk_fma_f32 v[228:229], v[140:141], v[56:57], v[228:229]
	v_pk_fma_f32 v[230:231], v[144:145], v[56:57], v[230:231]
	v_pk_fma_f32 v[232:233], v[148:149], v[56:57], v[232:233]
	v_pk_fma_f32 v[234:235], v[152:153], v[56:57], v[234:235]
	v_pk_fma_f32 v[236:237], v[156:157], v[56:57], v[236:237]
	v_pk_fma_f32 v[238:239], v[160:161], v[56:57], v[238:239]
	v_pk_fma_f32 v[240:241], v[164:165], v[56:57], v[240:241]
	v_pk_fma_f32 v[242:243], v[168:169], v[56:57], v[242:243]
	ds_read_b128 v[134:137], v1 offset:496
	ds_read_b128 v[138:141], v1 offset:4592
	ds_read_b128 v[142:145], v1 offset:8688
	ds_read_b128 v[146:149], v1 offset:12784
	ds_read_b128 v[150:153], v1 offset:16880
	ds_read_b128 v[154:157], v1 offset:20976
	ds_read_b128 v[158:161], v1 offset:25072
	ds_read_b128 v[162:165], v1 offset:29168
	ds_read_b128 v[166:169], v1 offset:33264
	s_waitcnt lgkmcnt(9)
	v_pk_fma_f32 v[226:227], v[98:99], v[58:59], v[226:227]
	v_pk_fma_f32 v[228:229], v[102:103], v[58:59], v[228:229]
	v_pk_fma_f32 v[230:231], v[106:107], v[58:59], v[230:231]
	v_pk_fma_f32 v[232:233], v[110:111], v[58:59], v[232:233]
	v_pk_fma_f32 v[234:235], v[114:115], v[58:59], v[234:235]
	v_pk_fma_f32 v[236:237], v[118:119], v[58:59], v[236:237]
	v_pk_fma_f32 v[238:239], v[122:123], v[58:59], v[238:239]
	v_pk_fma_f32 v[240:241], v[126:127], v[58:59], v[240:241]
	v_pk_fma_f32 v[242:243], v[130:131], v[58:59], v[242:243]
	v_pk_fma_f32 v[226:227], v[100:101], v[60:61], v[226:227]
	v_pk_fma_f32 v[228:229], v[104:105], v[60:61], v[228:229]
	v_pk_fma_f32 v[230:231], v[108:109], v[60:61], v[230:231]
	v_pk_fma_f32 v[232:233], v[112:113], v[60:61], v[232:233]
	v_pk_fma_f32 v[234:235], v[116:117], v[60:61], v[234:235]
	v_pk_fma_f32 v[236:237], v[120:121], v[60:61], v[236:237]
	v_pk_fma_f32 v[238:239], v[124:125], v[60:61], v[238:239]
	v_pk_fma_f32 v[240:241], v[128:129], v[60:61], v[240:241]
	v_pk_fma_f32 v[242:243], v[132:133], v[60:61], v[242:243]
	s_waitcnt lgkmcnt(0)
	v_pk_fma_f32 v[226:227], v[134:135], v[62:63], v[226:227]
	v_pk_fma_f32 v[228:229], v[138:139], v[62:63], v[228:229]
	v_pk_fma_f32 v[230:231], v[142:143], v[62:63], v[230:231]
	v_pk_fma_f32 v[232:233], v[146:147], v[62:63], v[232:233]
	v_pk_fma_f32 v[234:235], v[150:151], v[62:63], v[234:235]
	v_pk_fma_f32 v[236:237], v[154:155], v[62:63], v[236:237]
	v_pk_fma_f32 v[238:239], v[158:159], v[62:63], v[238:239]
	v_pk_fma_f32 v[240:241], v[162:163], v[62:63], v[240:241]
	v_pk_fma_f32 v[242:243], v[166:167], v[62:63], v[242:243]
	v_pk_fma_f32 v[226:227], v[136:137], v[64:65], v[226:227]
	v_pk_fma_f32 v[228:229], v[140:141], v[64:65], v[228:229]
	v_pk_fma_f32 v[230:231], v[144:145], v[64:65], v[230:231]
	v_pk_fma_f32 v[232:233], v[148:149], v[64:65], v[232:233]
	v_pk_fma_f32 v[234:235], v[152:153], v[64:65], v[234:235]
	v_pk_fma_f32 v[236:237], v[156:157], v[64:65], v[236:237]
	v_pk_fma_f32 v[238:239], v[160:161], v[64:65], v[238:239]
	v_pk_fma_f32 v[240:241], v[164:165], v[64:65], v[240:241]
	v_pk_fma_f32 v[242:243], v[168:169], v[64:65], v[242:243]
	v_add_f32_e32 v78, v226, v227
	v_add_f32_e32 v79, v228, v229
	v_add_f32_e32 v84, v230, v231
	v_add_f32_e32 v85, v232, v233
	v_add_f32_e32 v82, v234, v235
	v_add_f32_e32 v83, v236, v237
	v_add_f32_e32 v80, v238, v239
	v_add_f32_e32 v81, v240, v241
	v_add_f32_e32 v92, v242, v243
	ds_write2st64_b32 v91, v78, v79 offset1:1
	ds_write2st64_b32 v91, v84, v85 offset0:2 offset1:3
	ds_write2st64_b32 v91, v82, v83 offset0:4 offset1:5
	ds_write2st64_b32 v91, v80, v81 offset0:6 offset1:7
	ds_write_b32 v91, v92 offset:2048
	s_waitcnt lgkmcnt(0)
	s_barrier
	s_and_saveexec_b64 s[8:9], s[4:5]
	s_cbranch_execz .LBB0_1276
	s_mul_i32 s13, s12, 0x1800
	s_add_i32 s14, s13, s6
	v_or_b32_e32 v0, s14, v87
	v_ashrrev_i32_e32 v1, 31, v0
	s_mul_hi_i32 s13, s12, 9
	s_mul_i32 s12, s12, 9
	v_lshl_add_u64 v[0:1], v[0:1], 2, s[10:11]
	v_lshl_add_u64 v[2:3], s[6:7], 2, v[72:73]
	s_mov_b64 s[6:7], 0
	v_mov_b32_e32 v4, v196
